# r55 layout variant: NSA selected/sliding attention code shifted by 4 bytes, later code by 8 (code alignment tuning)
# baseline (speedup 1.0000x reference)
.LBB0_737:
	s_cmp_lg_u32 s81, s69
	s_cbranch_scc1 .LBB0_739
	v_mov_b32_e32 v1, v166
	s_nop 1
	v_permlane32_swap_b32_e32 v166, v1
	v_add_f32_e32 v1, v166, v1
	v_rcp_f32_e32 v2, v1
	v_cmp_lt_f32_e32 vcc, 0, v1
	v_mov_b32_e32 v14, v0
	v_mov_b32_e32 v15, v0
	v_cndmask_b32_e32 v1, 0, v2, vcc
	v_mul_f32_e32 v2, v156, v1
	v_pk_fma_f32 v[130:131], v[46:47], v[2:3], v[130:131] op_sel_hi:[1,0,1]
	v_pk_fma_f32 v[132:133], v[44:45], v[2:3], v[132:133] op_sel_hi:[1,0,1]
	v_pk_fma_f32 v[134:135], v[42:43], v[2:3], v[134:135] op_sel_hi:[1,0,1]
	v_pk_fma_f32 v[136:137], v[40:41], v[2:3], v[136:137] op_sel_hi:[1,0,1]
	v_pk_fma_f32 v[138:139], v[38:39], v[2:3], v[138:139] op_sel_hi:[1,0,1]
	v_pk_fma_f32 v[140:141], v[36:37], v[2:3], v[140:141] op_sel_hi:[1,0,1]
	v_pk_fma_f32 v[142:143], v[34:35], v[2:3], v[142:143] op_sel_hi:[1,0,1]
	v_pk_fma_f32 v[144:145], v[32:33], v[2:3], v[144:145] op_sel_hi:[1,0,1]
	v_pk_fma_f32 v[114:115], v[30:31], v[2:3], v[114:115] op_sel_hi:[1,0,1]
	v_pk_fma_f32 v[116:117], v[28:29], v[2:3], v[116:117] op_sel_hi:[1,0,1]
	v_pk_fma_f32 v[118:119], v[26:27], v[2:3], v[118:119] op_sel_hi:[1,0,1]
	v_pk_fma_f32 v[120:121], v[24:25], v[2:3], v[120:121] op_sel_hi:[1,0,1]
	v_pk_fma_f32 v[122:123], v[22:23], v[2:3], v[122:123] op_sel_hi:[1,0,1]
	v_pk_fma_f32 v[124:125], v[20:21], v[2:3], v[124:125] op_sel_hi:[1,0,1]
	v_pk_fma_f32 v[126:127], v[18:19], v[2:3], v[126:127] op_sel_hi:[1,0,1]
	v_pk_fma_f32 v[128:129], v[16:17], v[2:3], v[128:129] op_sel_hi:[1,0,1]
	v_mov_b32_e32 v1, v0
	v_mov_b32_e32 v2, v0
	v_mov_b32_e32 v3, v0
	v_mov_b32_e32 v4, v0
	v_mov_b32_e32 v5, v0
	v_mov_b32_e32 v6, v0
	v_mov_b32_e32 v7, v0
	v_mov_b32_e32 v8, v0
	v_mov_b32_e32 v9, v0
	v_mov_b32_e32 v10, v0
	v_mov_b32_e32 v11, v0
	v_mov_b32_e32 v12, v0
	v_mov_b32_e32 v13, v0
	v_mov_b64_e32 v[30:31], v[14:15]
	v_mov_b64_e32 v[46:47], v[14:15]
	v_mov_b32_e32 v105, 0
	v_mov_b32_e32 v160, 0xf149f2ca
	v_mov_b64_e32 v[28:29], v[12:13]
	v_mov_b64_e32 v[26:27], v[10:11]
	v_mov_b64_e32 v[24:25], v[8:9]
	v_mov_b64_e32 v[22:23], v[6:7]
	v_mov_b64_e32 v[20:21], v[4:5]
	v_mov_b64_e32 v[18:19], v[2:3]
	v_mov_b64_e32 v[16:17], v[0:1]
	v_mov_b64_e32 v[44:45], v[12:13]
	v_mov_b64_e32 v[42:43], v[10:11]
	v_mov_b64_e32 v[40:41], v[8:9]
	v_mov_b64_e32 v[38:39], v[6:7]
	v_mov_b64_e32 v[36:37], v[4:5]
	v_mov_b64_e32 v[34:35], v[2:3]
	v_mov_b64_e32 v[32:33], v[0:1]
	s_branch .LBB0_740
	s_nop 0

.LBB0_851:
	s_movk_i32 s86, 0x1000
	v_readlane_b32 s87, v253, 56
	v_readlane_b32 s41, v254, 25
	s_nop 7
	v_mov_b64_e32 v[48:49], v[16:17]
	v_mov_b64_e32 v[50:51], v[18:19]
	v_mov_b64_e32 v[52:53], v[20:21]
	v_mov_b64_e32 v[54:55], v[22:23]
	v_mov_b64_e32 v[56:57], v[24:25]
	v_mov_b64_e32 v[58:59], v[26:27]
	v_mov_b64_e32 v[60:61], v[28:29]
	v_mov_b64_e32 v[62:63], v[30:31]
	v_mov_b64_e32 v[64:65], v[32:33]
	v_mov_b64_e32 v[66:67], v[34:35]
	v_mov_b64_e32 v[68:69], v[36:37]
	v_mov_b64_e32 v[70:71], v[38:39]
	v_mov_b64_e32 v[72:73], v[40:41]
	v_mov_b64_e32 v[74:75], v[42:43]
	v_mov_b64_e32 v[76:77], v[44:45]
	v_mov_b64_e32 v[78:79], v[46:47]
	s_branch .LBB0_853
	s_nop 0
